# P2 queue order: all LRU chunk units first (level-major), then dilated attention, then MoBA longest-first
# speedup vs baseline: 1.0188x; 1.0188x over previous
; __device__ __forceinline__ void lru_unit(const Ctx& C, const Params& p, int l, int unit) {
;     ...
;             unsigned* pf = flg + (size_t)(unit - 64) * 16;
;             while (__hip_atomic_load(pf, __ATOMIC_RELAXED, __HIP_MEMORY_SCOPE_AGENT) == 0u) __builtin_amdgcn_s_sleep(2);
; __global__ void __launch_bounds__(512) hybrid_fwd(Params p) {
;     ...
;             if (C.tid == 0) s_unit = (int)atomicAdd(ctl + 64 * (1 + l), 1u);
;             __syncthreads();
;             const int u = s_unit;
;             __syncthreads();
;             if (u >= 1024 + 1024 + 512) break;
;             const int v2 = u - 512, grpq = v2 >> 7, rq = v2 & 127;
;     ...
;             if (u >= 512 && rq < 64) lru_unit(C, p, l, grpq * 64 + rq);
;     ...
;             if (u >= 512 && rq >= 64) moba_unit(C, grpq * 64 + (rq - 64), (const float*)(C.ws + WS_KM) + (size_t)l * 128 * 512);
.LBB0_321:
	s_or_b64 exec, exec, s[40:41]
	s_waitcnt lgkmcnt(0)
	s_barrier
	ds_read_b32 v0, v193
	s_movk_i32 s19, 0x9ff
	s_mov_b64 s[40:41], -1
	s_waitcnt lgkmcnt(0)
	s_barrier
	v_cmp_lt_i32_e32 vcc, s19, v0
	v_readfirstlane_b32 s74, v0
	s_cbranch_vccnz .LBB0_316
	s_cmp_lt_u32 s74, 1024
	s_cbranch_scc0 .Lq4_b
	s_lshr_b32 s19, s74, 6
	s_lshl_b32 s19, s19, 7
	s_and_b32 s20, s74, 63
	s_add_u32 s19, s19, s20
	s_add_u32 s74, s19, 512
	s_branch .Lq4_done
.Lq4_b:
	s_cmp_lt_u32 s74, 1536
	s_cbranch_scc0 .Lq4_c
	s_sub_u32 s74, s74, 1024
	s_branch .Lq4_done
.Lq4_c:
	s_sub_u32 s19, s74, 1536
	s_lshr_b32 s20, s19, 6
	s_lshl_b32 s20, s20, 7
	s_and_b32 s19, s19, 63
	s_add_u32 s19, s19, s20
	s_add_u32 s74, s19, 576
.Lq4_done:
	s_add_i32 s19, s74, 0xfffffe00
	s_ashr_i32 s72, s73, 6
	s_ashr_i32 s19, s19, 7
	s_and_b32 s20, s74, 0x7f
	s_cmpk_gt_i32 s74, 0x1ff
	s_cselect_b64 s[6:7], -1, 0
	s_cmp_lt_u32 s20, 64
	s_cselect_b64 s[22:23], -1, 0
	v_and_b32_e32 v169, 63, v132
	s_and_b64 s[22:23], s[6:7], s[22:23]
	s_andn2_b64 vcc, exec, s[22:23]
	v_lshrrev_b32_e32 v186, 4, v169
	s_cbranch_vccnz .LBB0_381
	s_cmp_lg_u32 s72, 0
	s_cbranch_scc1 .Llru_pf1_skip
	s_cmp_lt_i32 s19, 1
	s_cbranch_scc1 .Llru_pf1_skip
	s_lshl_b32 s100, s19, 6
	s_or_b32 s100, s100, s20
	s_sub_i32 s100, s100, 64
	s_lshl_b32 s100, s100, 6
	s_add_u32 s100, s100, s64
	s_addc_u32 s101, s65, 0
	s_add_u32 s100, s100, s8
	s_addc_u32 s101, s101, s9
	s_add_u32 s100, s100, 0x180000
	s_addc_u32 s101, s101, 0
	global_load_dword v206, v193, s[100:101] sc1
